# FFN-up meta-row tail unit: second K-group operand loads issued together with the first (fresh registers), one wait instead of two; on v36
# baseline (speedup 1.0000x reference)
.LBB0_954:
	s_and_b32 s17, s3, 0xffffff00
	s_and_b32 s16, s1, 0x60
	v_or_b32_e32 v2, s17, v1
	v_or_b32_e32 v2, s16, v2
	v_ashrrev_i32_e32 v3, 31, v2
	v_lshlrev_b64 v[2:3], 11, v[2:3]
	v_lshl_add_u64 v[86:87], v[36:37], 0, v[2:3]
	global_load_dwordx4 v[18:21], v[34:35], off
	global_load_dwordx4 v[2:5], v[86:87], off
	v_add_co_u32_e32 v90, vcc, 0x40000, v86
	s_ashr_i32 s17, s0, 2
	s_nop 0
	v_addc_co_u32_e32 v91, vcc, 0, v87, vcc
	global_load_dwordx4 v[22:25], v[90:91], off
	global_load_dwordx4 v[46:49], v[34:35], off offset:32
	global_load_dwordx4 v[50:53], v[86:87], off offset:32
	global_load_dwordx4 v[54:57], v[90:91], off offset:32
	global_load_dwordx4 v[58:61], v[34:35], off offset:64
	global_load_dwordx4 v[62:65], v[86:87], off offset:64
	global_load_dwordx4 v[66:69], v[90:91], off offset:64
	global_load_dwordx4 v[70:73], v[34:35], off offset:96
	global_load_dwordx4 v[74:77], v[86:87], off offset:96
	global_load_dwordx4 v[78:81], v[90:91], off offset:96
	global_load_dwordx4 v[114:117], v[34:35], off offset:128
	global_load_dwordx4 v[118:121], v[86:87], off offset:128
	global_load_dwordx4 v[122:125], v[90:91], off offset:128
	global_load_dwordx4 v[126:129], v[34:35], off offset:160
	global_load_dwordx4 v[130:133], v[86:87], off offset:160
	global_load_dwordx4 v[134:137], v[90:91], off offset:160
	global_load_dwordx4 v[138:141], v[34:35], off offset:192
	global_load_dwordx4 v[142:145], v[86:87], off offset:192
	global_load_dwordx4 v[146:149], v[90:91], off offset:192
	global_load_dwordx4 v[150:153], v[34:35], off offset:224
	global_load_dwordx4 v[154:157], v[86:87], off offset:224
	global_load_dwordx4 v[158:161], v[90:91], off offset:224
	s_lshl_b32 s18, s17, 8
	s_or_b32 s18, s18, s16
	s_lshl_b32 s17, s17, 7
	s_or_b32 s16, s17, s16
	s_addk_i32 s1, 0x2000
	s_addk_i32 s3, 0x4000
	s_waitcnt vmcnt(0) lgkmcnt(0)
	v_mfma_f32_32x32x16_bf16 v[2:17], v[18:21], v[2:5], 0
	v_mfma_f32_32x32x16_bf16 v[18:33], v[18:21], v[22:25], 0
	v_mfma_f32_32x32x16_bf16 v[2:17], v[46:49], v[50:53], v[2:17]
	v_mfma_f32_32x32x16_bf16 v[18:33], v[46:49], v[54:57], v[18:33]
	v_mfma_f32_32x32x16_bf16 v[2:17], v[58:61], v[62:65], v[2:17]
	v_mfma_f32_32x32x16_bf16 v[18:33], v[58:61], v[66:69], v[18:33]
	v_mfma_f32_32x32x16_bf16 v[2:17], v[70:73], v[74:77], v[2:17]
	v_mfma_f32_32x32x16_bf16 v[18:33], v[70:73], v[78:81], v[18:33]
	s_nop 0
	s_nop 0
	s_waitcnt vmcnt(0) lgkmcnt(0)
	v_mfma_f32_32x32x16_bf16 v[2:17], v[114:117], v[118:121], v[2:17]
	v_mfma_f32_32x32x16_bf16 v[18:33], v[114:117], v[122:125], v[18:33]
	v_or_b32_e32 v46, s18, v43
	v_ashrrev_i32_e32 v47, 31, v46
	v_lshlrev_b64 v[94:95], 3, v[46:47]
	v_lshl_add_u64 v[96:97], s[10:11], 0, v[94:95]
	v_lshl_add_u64 v[94:95], s[12:13], 0, v[94:95]
	global_load_dwordx4 v[98:101], v[96:97], off
	global_load_dwordx4 v[102:105], v[94:95], off
	global_load_dwordx4 v[106:109], v[96:97], off offset:1024
	global_load_dwordx4 v[110:113], v[94:95], off offset:1024
	v_mfma_f32_32x32x16_bf16 v[2:17], v[126:129], v[130:133], v[2:17]
	v_mfma_f32_32x32x16_bf16 v[18:33], v[126:129], v[134:137], v[18:33]
	v_mfma_f32_32x32x16_bf16 v[2:17], v[138:141], v[142:145], v[2:17]
	v_mfma_f32_32x32x16_bf16 v[18:33], v[138:141], v[146:149], v[18:33]
	v_mfma_f32_32x32x16_bf16 v[2:17], v[150:153], v[154:157], v[2:17]
	v_mfma_f32_32x32x16_bf16 v[18:33], v[150:153], v[158:161], v[18:33]
	s_nop 11
	ds_write2_b32 v42, v2, v18 offset1:32
	ds_write2_b32 v42, v3, v19 offset0:64 offset1:96
	ds_write2_b32 v42, v4, v20 offset0:128 offset1:160
	ds_write2_b32 v42, v5, v21 offset0:192 offset1:224
	v_add_u32_e32 v2, 0x800, v42
	ds_write2_b32 v2, v6, v22 offset1:32
	ds_write2_b32 v2, v7, v23 offset0:64 offset1:96
	ds_write2_b32 v2, v8, v24 offset0:128 offset1:160
	ds_write2_b32 v2, v9, v25 offset0:192 offset1:224
	v_add_u32_e32 v2, 0x1000, v42
	ds_write2_b32 v2, v10, v26 offset1:32
	ds_write2_b32 v2, v11, v27 offset0:64 offset1:96
	ds_write2_b32 v2, v12, v28 offset0:128 offset1:160
	ds_write2_b32 v2, v13, v29 offset0:192 offset1:224
	v_add_u32_e32 v2, 0x1800, v42
	ds_write2_b32 v2, v14, v30 offset1:32
	ds_write2_b32 v2, v15, v31 offset0:64 offset1:96
	ds_write2_b32 v2, v16, v32 offset0:128 offset1:160
	ds_write2_b32 v2, v17, v33 offset0:192 offset1:224
	s_waitcnt lgkmcnt(0)
	s_barrier
	ds_read2_b64 v[2:5], v44 offset1:16
	s_waitcnt lgkmcnt(0)
	v_pk_add_f32 v[32:33], v[4:5], 0 op_sel_hi:[1,0]
	v_add_u32_e32 v4, 0x2000, v44
	ds_read2_b64 v[12:15], v4 offset1:16
	global_load_dwordx4 v[4:7], v[38:39], off
	global_load_dwordx4 v[8:11], v[38:39], off offset:16
	global_load_dwordx4 v[16:19], v[38:39], off offset:32
	global_load_dwordx4 v[20:23], v[38:39], off offset:48
	global_load_dwordx4 v[24:27], v[38:39], off offset:64
	global_load_dwordx4 v[28:31], v[38:39], off offset:80
	v_pk_add_f32 v[2:3], v[2:3], 0 op_sel_hi:[1,0]
	s_waitcnt vmcnt(0) lgkmcnt(0)
	v_pk_add_f32 v[4:5], v[4:5], v[6:7]
	s_nop 0
	v_pk_add_f32 v[4:5], v[4:5], 0 op_sel_hi:[1,0]
	v_pk_add_f32 v[6:7], v[8:9], v[10:11]
	v_pk_add_f32 v[12:13], v[2:3], v[12:13]
	v_add_f32_e32 v49, v25, v27
	v_mov_b32_e32 v25, v28
	v_mov_b32_e32 v27, v30
	v_pk_add_f32 v[50:51], v[24:25], v[26:27]
	v_add_f32_e32 v53, v29, v31
	global_load_dwordx4 v[24:27], v[38:39], off offset:96
	global_load_dwordx4 v[28:31], v[38:39], off offset:112
	v_pk_add_f32 v[4:5], v[4:5], v[6:7]
	v_pk_add_f32 v[6:7], v[16:17], v[18:19]
	v_mov_b32_e32 v48, v50
	v_pk_add_f32 v[4:5], v[4:5], v[6:7]
	v_pk_add_f32 v[6:7], v[20:21], v[22:23]
	v_mov_b32_e32 v52, v51
	v_pk_add_f32 v[4:5], v[4:5], v[6:7]
	v_pk_add_f32 v[18:19], v[32:33], v[14:15]
	v_pk_add_f32 v[4:5], v[4:5], v[48:49]
	v_lshlrev_b64 v[8:9], 3, v[46:47]
	v_pk_add_f32 v[4:5], v[4:5], v[52:53]
	v_lshl_add_u64 v[10:11], s[10:11], 0, v[8:9]
	v_lshl_add_u64 v[8:9], s[12:13], 0, v[8:9]
	v_or_b32_e32 v2, s16, v43
	s_add_i32 s16, s0, 0x100
	s_cmpk_lt_i32 s0, 0xff58
	s_mov_b32 s0, s16
	s_waitcnt vmcnt(0) lgkmcnt(0)
	v_add_f32_e32 v55, v25, v27
	v_mov_b32_e32 v25, v28
	v_mov_b32_e32 v27, v30
	v_pk_add_f32 v[24:25], v[24:25], v[26:27]
	v_add_f32_e32 v27, v29, v31
	v_mov_b32_e32 v54, v24
	v_pk_add_f32 v[4:5], v[4:5], v[54:55]
	v_mov_b32_e32 v26, v25
	v_pk_add_f32 v[4:5], v[4:5], v[26:27]
	s_nop 0
	v_pk_mul_f32 v[6:7], v[4:5], s[64:65] op_sel_hi:[1,0]
	s_nop 0
	v_fma_f32 v3, -v6, v6, v7
	v_max_f32_e32 v3, 0, v3
	v_add_f32_e32 v3, 0x3727c5ac, v3
	v_cmp_gt_f32_e32 vcc, s35, v3
	v_mul_f32_e32 v4, 0x4b800000, v3
	s_nop 0
	v_cndmask_b32_e32 v3, v3, v4, vcc
	v_rsq_f32_e32 v3, v3
	s_nop 0
	v_mul_f32_e32 v4, 0x45800000, v3
	v_cndmask_b32_e32 v4, v3, v4, vcc
	v_add_u32_e32 v3, 0x4000, v44
	ds_read2_b64 v[14:17], v3 offset1:16
	v_add_u32_e32 v3, 0x6000, v44
	s_waitcnt lgkmcnt(0)
	v_pk_add_f32 v[20:21], v[12:13], v[14:15]
	ds_read2_b64 v[12:15], v3 offset1:16
	v_pk_add_f32 v[16:17], v[18:19], v[16:17]
	v_add_u32_e32 v3, 0x8000, v44
	s_waitcnt lgkmcnt(0)
	v_pk_add_f32 v[18:19], v[20:21], v[12:13]
	v_pk_add_f32 v[16:17], v[16:17], v[14:15]
	ds_read2_b64 v[12:15], v3 offset1:16
	v_add_u32_e32 v3, 0xa000, v44
	s_waitcnt lgkmcnt(0)
	v_pk_add_f32 v[18:19], v[18:19], v[12:13]
	v_pk_add_f32 v[16:17], v[16:17], v[14:15]
	ds_read2_b64 v[12:15], v3 offset1:16
	v_add_u32_e32 v3, 0xc000, v44
	s_waitcnt lgkmcnt(0)
	v_pk_add_f32 v[18:19], v[18:19], v[12:13]
	v_pk_add_f32 v[16:17], v[16:17], v[14:15]
	ds_read2_b64 v[12:15], v3 offset1:16
	v_add_u32_e32 v3, 0xe000, v44
	s_waitcnt lgkmcnt(0)
	v_pk_add_f32 v[18:19], v[18:19], v[12:13]
	v_pk_add_f32 v[16:17], v[16:17], v[14:15]
	ds_read2_b64 v[12:15], v3 offset1:16
	s_waitcnt lgkmcnt(0)
	v_pk_add_f32 v[18:19], v[18:19], v[12:13]
	v_pk_add_f32 v[16:17], v[16:17], v[14:15]
	v_mov_b64_e32 v[12:13], v[98:99]
	v_mov_b64_e32 v[14:15], v[100:101]
	s_waitcnt vmcnt(0) lgkmcnt(0)
	v_cvt_f64_i32_e32 v[20:21], v15
	v_ldexp_f64 v[20:21], v[20:21], 32
	v_cvt_f64_u32_e32 v[14:15], v14
	v_add_f64 v[14:15], v[20:21], v[14:15]
	v_cvt_f64_i32_e32 v[20:21], v13
	v_ldexp_f64 v[20:21], v[20:21], 32
	v_cvt_f64_u32_e32 v[12:13], v12
	v_add_f64 v[12:13], v[20:21], v[12:13]
	v_ldexp_f64 v[12:13], v[12:13], s2
	v_ldexp_f64 v[14:15], v[14:15], s2
	v_cvt_f32_f64_e32 v15, v[14:15]
	v_cvt_f32_f64_e32 v14, v[12:13]
	v_pk_fma_f32 v[18:19], v[6:7], v[14:15], v[18:19] op_sel_hi:[0,1,1] neg_lo:[1,0,0] neg_hi:[1,0,0]
	v_mov_b64_e32 v[12:13], v[102:103]
	v_mov_b64_e32 v[14:15], v[104:105]
	s_waitcnt vmcnt(0) lgkmcnt(0)
	v_cvt_f64_i32_e32 v[20:21], v15
	v_ldexp_f64 v[20:21], v[20:21], 32
	v_cvt_f64_u32_e32 v[14:15], v14
	v_add_f64 v[14:15], v[20:21], v[14:15]
	v_cvt_f64_i32_e32 v[20:21], v13
	v_ldexp_f64 v[20:21], v[20:21], 32
	v_cvt_f64_u32_e32 v[12:13], v12
	v_add_f64 v[12:13], v[20:21], v[12:13]
	v_ldexp_f64 v[12:13], v[12:13], s2
	v_ldexp_f64 v[14:15], v[14:15], s2
	v_cvt_f32_f64_e32 v15, v[14:15]
	v_cvt_f32_f64_e32 v14, v[12:13]
	v_mov_b64_e32 v[10:11], v[106:107]
	v_mov_b64_e32 v[12:13], v[108:109]
	v_pk_fma_f32 v[14:15], v[18:19], v[4:5], v[14:15] op_sel_hi:[1,0,1]
	s_waitcnt vmcnt(0) lgkmcnt(0)
	v_cvt_f64_i32_e32 v[18:19], v13
	v_ldexp_f64 v[18:19], v[18:19], 32
	v_cvt_f64_u32_e32 v[12:13], v12
	v_add_f64 v[12:13], v[18:19], v[12:13]
	v_cvt_f64_i32_e32 v[18:19], v11
	v_ldexp_f64 v[18:19], v[18:19], 32
	v_cvt_f64_u32_e32 v[10:11], v10
	v_add_f64 v[10:11], v[18:19], v[10:11]
	v_ldexp_f64 v[10:11], v[10:11], s2
	v_ldexp_f64 v[12:13], v[12:13], s2
	v_cvt_f32_f64_e32 v13, v[12:13]
	v_cvt_f32_f64_e32 v12, v[10:11]
	v_pk_fma_f32 v[10:11], v[6:7], v[12:13], v[16:17] op_sel_hi:[0,1,1] neg_lo:[1,0,0] neg_hi:[1,0,0]
	v_mov_b64_e32 v[6:7], v[110:111]
	v_mov_b64_e32 v[8:9], v[112:113]
	v_mul_f32_e32 v3, 0xbfb8aa3b, v14
	v_exp_f32_e32 v3, v3
	s_waitcnt vmcnt(0) lgkmcnt(0)
	v_cvt_f64_i32_e32 v[12:13], v9
	v_ldexp_f64 v[12:13], v[12:13], 32
	v_cvt_f64_u32_e32 v[8:9], v8
	v_add_f64 v[8:9], v[12:13], v[8:9]
	v_cvt_f64_i32_e32 v[12:13], v7
	v_ldexp_f64 v[12:13], v[12:13], 32
	v_cvt_f64_u32_e32 v[6:7], v6
	v_add_f64 v[6:7], v[12:13], v[6:7]
	v_ldexp_f64 v[6:7], v[6:7], s2
	v_ldexp_f64 v[8:9], v[8:9], s2
	v_add_f32_e32 v3, 1.0, v3
	v_cvt_f32_f64_e32 v9, v[8:9]
	v_cvt_f32_f64_e32 v8, v[6:7]
	v_rcp_f32_e32 v6, v3
	v_mul_f32_e32 v3, 0xbfb8aa3b, v15
	v_exp_f32_e32 v3, v3
	v_pk_fma_f32 v[4:5], v[10:11], v[4:5], v[8:9] op_sel_hi:[1,0,1]
	v_add_f32_e32 v3, 1.0, v3
	v_rcp_f32_e32 v7, v3
	v_ashrrev_i32_e32 v3, 31, v2
	v_lshl_add_u64 v[2:3], v[2:3], 1, v[40:41]
	v_pk_mul_f32 v[6:7], v[14:15], v[6:7]
	s_nop 0
	v_pk_mul_f32 v[4:5], v[4:5], v[6:7]
	s_nop 0
	v_cvt_pk_bf16_f32 v4, v4, v5
	global_store_dword v[2:3], v4, off sc1
	s_waitcnt vmcnt(0) lgkmcnt(0)
	s_barrier
	s_cmp_lg_u32 s86, 0
	s_cbranch_scc1 .Ltail_sig_skip
	v_mov_b32_e32 v18, 0x3d00
	s_mov_b64 exec, 1
	global_atomic_add v18, v223, s[90:91]
	s_mov_b64 exec, -1
